# NSA selected-block tiles: second tile copy without the 16 causal-limit compares for blocks fully in the past
# baseline (speedup 1.0000x reference)
.LBB0_1997:
	s_lshr_b32 s0, s2, 5
	s_cmp_eq_u32 s0, 1
	s_cselect_b64 vcc, -1, 0
	s_cmp_eq_u32 s0, 2
	v_cndmask_b32_e32 v100, v80, v81, vcc
	s_cselect_b64 vcc, -1, 0
	s_cmp_eq_u32 s0, 3
	v_cndmask_b32_e32 v100, v100, v82, vcc
	s_cselect_b64 vcc, -1, 0
	v_cndmask_b32_e32 v100, v100, v83, vcc
	s_and_b32 s3, s2, 31
	v_bfe_u32 v100, v100, s3, 1
	v_cmp_ne_u32_e32 vcc, 0, v100
	s_nop 1
	s_mov_b64 s[0:1], vcc
	s_cbranch_vccz .LBB0_1992
	s_lshl_b32 s3, s2, 6
	v_subrev_u32_e32 v230, s3, v120
	v_cmp_gt_i32_e32 vcc, 63, v230
	s_nop 1
	s_and_b64 vcc, vcc, s[0:1]
	s_cbranch_vccz .Lsf_entry
	s_lshl_b32 s2, s2, 6
	ds_read_b128 v[100:103], v245
	ds_read_b128 v[104:107], v245 offset:64
	s_waitcnt lgkmcnt(1)
	v_mfma_f32_16x16x32_bf16 v[108:111], v[100:103], v[20:23], v[220:223]
	v_mfma_f32_16x16x32_bf16 v[100:103], v[100:103], v[28:31], v[224:227]
	s_waitcnt lgkmcnt(0)
	v_mfma_f32_16x16x32_bf16 v[108:111], v[104:107], v[24:27], v[108:111]
	v_mfma_f32_16x16x32_bf16 v[100:103], v[104:107], v[32:35], v[100:103]
	ds_read_b128 v[104:107], v245 offset:2304
	ds_read_b128 v[112:115], v245 offset:2368
	ds_read_b128 v[132:135], v245 offset:4608
	ds_read_b128 v[152:155], v245 offset:4672
	s_waitcnt lgkmcnt(3)
	v_mfma_f32_16x16x32_bf16 v[124:127], v[104:107], v[20:23], v[220:223]
	v_mfma_f32_16x16x32_bf16 v[104:107], v[104:107], v[28:31], v[224:227]
	s_waitcnt lgkmcnt(2)
	v_mfma_f32_16x16x32_bf16 v[138:141], v[112:115], v[24:27], v[124:127]
	s_nop 4
	v_subrev_u32_e32 v124, s2, v120
	v_mfma_f32_16x16x32_bf16 v[104:107], v[112:115], v[32:35], v[104:107]
	ds_read_b128 v[112:115], v245 offset:6912
	ds_read_b128 v[156:159], v245 offset:6976
	v_cndmask_b32_e64 v124, -1, v124, s[0:1]
	v_sub_u32_e32 v136, v124, v248
	s_waitcnt lgkmcnt(3)
	v_mfma_f32_16x16x32_bf16 v[164:167], v[132:135], v[20:23], v[220:223]
	v_cmp_gt_i32_e64 s[0:1], 0, v136
	v_cmp_gt_i32_e64 s[2:3], 1, v136
	v_cmp_gt_i32_e64 s[4:5], 2, v136
	v_mfma_f32_16x16x32_bf16 v[168:171], v[132:135], v[28:31], v[224:227]
	v_cmp_gt_i32_e64 s[6:7], 3, v136
	v_cndmask_b32_e64 v127, v108, v207, s[0:1]
	v_cndmask_b32_e64 v131, v109, v207, s[2:3]
	v_cndmask_b32_e64 v133, v110, v207, s[4:5]
	v_cndmask_b32_e64 v135, v111, v207, s[6:7]
	s_waitcnt lgkmcnt(2)
	v_mfma_f32_16x16x32_bf16 v[164:167], v[152:155], v[24:27], v[164:167]
	v_cmp_gt_i32_e64 s[8:9], 4, v136
	v_cmp_gt_i32_e64 s[10:11], 5, v136
	v_cmp_gt_i32_e64 s[14:15], 6, v136
	v_mfma_f32_16x16x32_bf16 v[108:111], v[152:155], v[32:35], v[168:171]
	v_cmp_gt_i32_e64 s[16:17], 7, v136
	v_cndmask_b32_e64 v137, v138, v207, s[8:9]
	v_cndmask_b32_e64 v138, v139, v207, s[10:11]
	s_waitcnt lgkmcnt(1)
	v_mfma_f32_16x16x32_bf16 v[152:155], v[112:115], v[20:23], v[220:223]
	v_cndmask_b32_e64 v139, v140, v207, s[14:15]
	v_cndmask_b32_e64 v140, v141, v207, s[16:17]
	v_max_f32_e32 v141, v131, v127
	s_waitcnt lgkmcnt(0)
	v_mfma_f32_16x16x32_bf16 v[152:155], v[156:159], v[24:27], v[152:155]
	v_max3_f32 v141, v141, v133, v135
	v_cmp_gt_i32_e64 s[18:19], 32, v136
	v_cmp_gt_i32_e64 s[20:21], 33, v136
	v_max3_f32 v141, v141, v137, v138
	v_cndmask_b32_e64 v123, v164, v207, s[18:19]
	v_cndmask_b32_e64 v124, v165, v207, s[20:21]
	v_mfma_f32_16x16x32_bf16 v[112:115], v[112:115], v[28:31], v[224:227]
	v_cmp_gt_i32_e64 s[22:23], 34, v136
	v_cmp_gt_i32_e64 s[24:25], 35, v136
	v_max3_f32 v141, v141, v139, v140
	v_cndmask_b32_e64 v125, v166, v207, s[22:23]
	v_cndmask_b32_e64 v126, v167, v207, s[24:25]
	v_cmp_gt_i32_e64 s[26:27], 36, v136
	v_cmp_gt_i32_e64 s[28:29], 37, v136
	v_max3_f32 v141, v141, v123, v124
	v_cndmask_b32_e64 v130, v152, v207, s[26:27]
	v_cndmask_b32_e64 v132, v153, v207, s[28:29]
	v_cmp_gt_i32_e64 s[30:31], 38, v136
	v_cmp_gt_i32_e64 s[34:35], 39, v136
	v_max3_f32 v141, v141, v125, v126
	v_cndmask_b32_e64 v134, v154, v207, s[30:31]
	v_cndmask_b32_e64 v136, v155, v207, s[34:35]
	v_max3_f32 v141, v141, v130, v132
	v_mfma_f32_16x16x32_bf16 v[112:115], v[156:159], v[32:35], v[112:115]
	v_max3_f32 v141, v141, v134, v136
	v_sub_f32_e32 v142, v141, v228

	v_cmp_lt_f32_e32 vcc, s42, v142
	s_cbranch_vccz .LBB0_2003
	v_mov_b32_e32 v142, v141
	s_nop 1
	v_permlane16_swap_b32_e32 v141, v142
	v_max_f32_e32 v141, v142, v141
	v_mov_b32_e32 v142, v141
	s_nop 1
	v_permlane32_swap_b32_e32 v141, v142
	v_max3_f32 v142, v228, v141, v142
	v_sub_f32_e32 v116, v228, v142

	v_exp_f32_e32 v116, v116
	v_mov_b32_e32 v143, v117
	v_mul_f32_e32 v118, v118, v116
	v_pk_mul_f32 v[50:51], v[50:51], v[116:117] op_sel_hi:[1,0]
	v_pk_mul_f32 v[48:49], v[48:49], v[116:117] op_sel_hi:[1,0]
	v_pk_mul_f32 v[54:55], v[54:55], v[116:117] op_sel_hi:[1,0]
	v_pk_mul_f32 v[52:53], v[52:53], v[116:117] op_sel_hi:[1,0]
	v_pk_mul_f32 v[58:59], v[58:59], v[116:117] op_sel_hi:[1,0]
	v_pk_mul_f32 v[56:57], v[56:57], v[116:117] op_sel_hi:[1,0]
	v_pk_mul_f32 v[62:63], v[62:63], v[116:117] op_sel_hi:[1,0]
	v_pk_mul_f32 v[60:61], v[60:61], v[116:117] op_sel_hi:[1,0]
	v_mul_f32_e32 v116, -1.0, v142
	v_fmamk_f32 v117, v127, 0x3f800000, v116
	v_exp_f32_e32 v127, v117
	v_fmamk_f32 v117, v131, 0x3f800000, v116
	v_exp_f32_e32 v131, v117
	v_fmamk_f32 v117, v133, 0x3f800000, v116
	v_exp_f32_e32 v133, v117
	v_fmamk_f32 v117, v135, 0x3f800000, v116
	v_exp_f32_e32 v135, v117
	v_fmamk_f32 v137, v137, 0x3f800000, v116
	v_add_f32_e32 v117, 0, v127
	v_exp_f32_e32 v137, v137
	v_fmamk_f32 v138, v138, 0x3f800000, v116
	v_add_f32_e32 v117, v131, v117
	v_exp_f32_e32 v138, v138
	v_fmamk_f32 v139, v139, 0x3f800000, v116
	v_add_f32_e32 v117, v133, v117
	v_exp_f32_e32 v139, v139
	v_fmamk_f32 v140, v140, 0x3f800000, v116
	v_add_f32_e32 v117, v135, v117
	v_exp_f32_e32 v140, v140
	v_fmamk_f32 v123, v123, 0x3f800000, v116
	v_add_f32_e32 v117, v137, v117
	v_exp_f32_e32 v123, v123
	v_fmamk_f32 v124, v124, 0x3f800000, v116
	v_add_f32_e32 v117, v138, v117
	v_exp_f32_e32 v124, v124
	v_fmamk_f32 v125, v125, 0x3f800000, v116
	v_add_f32_e32 v117, v139, v117
	v_exp_f32_e32 v125, v125
	v_fmamk_f32 v126, v126, 0x3f800000, v116
	v_add_f32_e32 v117, v140, v117
	v_exp_f32_e32 v126, v126
	v_fmamk_f32 v130, v130, 0x3f800000, v116
	v_add_f32_e32 v117, v123, v117
	v_exp_f32_e32 v130, v130
	v_fmamk_f32 v132, v132, 0x3f800000, v116
	v_add_f32_e32 v117, v124, v117
	v_exp_f32_e32 v132, v132
	v_fmamk_f32 v134, v134, 0x3f800000, v116
	v_add_f32_e32 v117, v125, v117
	v_exp_f32_e32 v134, v134
	v_fmac_f32_e32 v116, 1.0, v136
	v_add_f32_e32 v117, v126, v117
	v_exp_f32_e32 v136, v116
	v_add_f32_e32 v116, v130, v117
	v_add_f32_e32 v116, v132, v116
	v_add_f32_e32 v116, v134, v116
	v_add_f32_e32 v141, v136, v116
	v_cmp_lt_f32_e32 vcc, 0xec4ecb8f, v142
	v_sub_f32_e32 v230, v142, v220
	s_nop 0
	v_cndmask_b32_e32 v231, 0, v142, vcc
	v_mov_b32_e32 v116, v230
	v_cndmask_b32_e64 v228, v228, 0, vcc
	v_sub_f32_e32 v220, v220, v231
	v_sub_f32_e32 v221, v221, v231
	v_sub_f32_e32 v222, v222, v231
	v_sub_f32_e32 v223, v223, v231
	s_branch .LBB0_2004

.Lsf_entry:
	s_not_b64 s[4:5], s[0:1]
	s_lshl_b32 s2, s2, 6
	ds_read_b128 v[100:103], v245
	ds_read_b128 v[104:107], v245 offset:64
	s_waitcnt lgkmcnt(1)
	v_mfma_f32_16x16x32_bf16 v[108:111], v[100:103], v[20:23], v[220:223]
	v_mfma_f32_16x16x32_bf16 v[100:103], v[100:103], v[28:31], v[224:227]
	s_waitcnt lgkmcnt(0)
	v_mfma_f32_16x16x32_bf16 v[108:111], v[104:107], v[24:27], v[108:111]
	v_mfma_f32_16x16x32_bf16 v[100:103], v[104:107], v[32:35], v[100:103]
	ds_read_b128 v[104:107], v245 offset:2304
	ds_read_b128 v[112:115], v245 offset:2368
	ds_read_b128 v[132:135], v245 offset:4608
	ds_read_b128 v[152:155], v245 offset:4672
	s_waitcnt lgkmcnt(3)
	v_mfma_f32_16x16x32_bf16 v[124:127], v[104:107], v[20:23], v[220:223]
	v_mfma_f32_16x16x32_bf16 v[104:107], v[104:107], v[28:31], v[224:227]
	s_waitcnt lgkmcnt(2)
	v_mfma_f32_16x16x32_bf16 v[138:141], v[112:115], v[24:27], v[124:127]
	s_nop 4
	v_mfma_f32_16x16x32_bf16 v[104:107], v[112:115], v[32:35], v[104:107]
	ds_read_b128 v[112:115], v245 offset:6912
	ds_read_b128 v[156:159], v245 offset:6976
	s_waitcnt lgkmcnt(3)
	v_mfma_f32_16x16x32_bf16 v[164:167], v[132:135], v[20:23], v[220:223]
	v_mfma_f32_16x16x32_bf16 v[168:171], v[132:135], v[28:31], v[224:227]
	v_cndmask_b32_e64 v127, v108, v207, s[4:5]
	v_cndmask_b32_e64 v131, v109, v207, s[4:5]
	v_cndmask_b32_e64 v133, v110, v207, s[4:5]
	v_cndmask_b32_e64 v135, v111, v207, s[4:5]
	s_waitcnt lgkmcnt(2)
	v_mfma_f32_16x16x32_bf16 v[164:167], v[152:155], v[24:27], v[164:167]
	v_mfma_f32_16x16x32_bf16 v[108:111], v[152:155], v[32:35], v[168:171]
	v_cndmask_b32_e64 v137, v138, v207, s[4:5]
	v_cndmask_b32_e64 v138, v139, v207, s[4:5]
	s_waitcnt lgkmcnt(1)
	v_mfma_f32_16x16x32_bf16 v[152:155], v[112:115], v[20:23], v[220:223]
	v_cndmask_b32_e64 v139, v140, v207, s[4:5]
	v_cndmask_b32_e64 v140, v141, v207, s[4:5]
	v_max_f32_e32 v141, v131, v127
	s_waitcnt lgkmcnt(0)
	v_mfma_f32_16x16x32_bf16 v[152:155], v[156:159], v[24:27], v[152:155]
	v_max3_f32 v141, v141, v133, v135
	v_max3_f32 v141, v141, v137, v138
	v_cndmask_b32_e64 v123, v164, v207, s[4:5]
	v_cndmask_b32_e64 v124, v165, v207, s[4:5]
	v_mfma_f32_16x16x32_bf16 v[112:115], v[112:115], v[28:31], v[224:227]
	v_max3_f32 v141, v141, v139, v140
	v_cndmask_b32_e64 v125, v166, v207, s[4:5]
	v_cndmask_b32_e64 v126, v167, v207, s[4:5]
	v_max3_f32 v141, v141, v123, v124
	v_cndmask_b32_e64 v130, v152, v207, s[4:5]
	v_cndmask_b32_e64 v132, v153, v207, s[4:5]
	v_max3_f32 v141, v141, v125, v126
	v_cndmask_b32_e64 v134, v154, v207, s[4:5]
	v_cndmask_b32_e64 v136, v155, v207, s[4:5]
	v_max3_f32 v141, v141, v130, v132
	v_mfma_f32_16x16x32_bf16 v[112:115], v[156:159], v[32:35], v[112:115]
	v_max3_f32 v141, v141, v134, v136
	v_sub_f32_e32 v142, v141, v228

	v_cmp_lt_f32_e32 vcc, s42, v142
	s_cbranch_vccz .Lsf_2003
	v_mov_b32_e32 v142, v141
	s_nop 1
	v_permlane16_swap_b32_e32 v141, v142
	v_max_f32_e32 v141, v142, v141
	v_mov_b32_e32 v142, v141
	s_nop 1
	v_permlane32_swap_b32_e32 v141, v142
	v_max3_f32 v142, v228, v141, v142
	v_sub_f32_e32 v116, v228, v142

	v_exp_f32_e32 v116, v116
	v_mov_b32_e32 v143, v117
	v_mul_f32_e32 v118, v118, v116
	v_pk_mul_f32 v[50:51], v[50:51], v[116:117] op_sel_hi:[1,0]
	v_pk_mul_f32 v[48:49], v[48:49], v[116:117] op_sel_hi:[1,0]
	v_pk_mul_f32 v[54:55], v[54:55], v[116:117] op_sel_hi:[1,0]
	v_pk_mul_f32 v[52:53], v[52:53], v[116:117] op_sel_hi:[1,0]
	v_pk_mul_f32 v[58:59], v[58:59], v[116:117] op_sel_hi:[1,0]
	v_pk_mul_f32 v[56:57], v[56:57], v[116:117] op_sel_hi:[1,0]
	v_pk_mul_f32 v[62:63], v[62:63], v[116:117] op_sel_hi:[1,0]
	v_pk_mul_f32 v[60:61], v[60:61], v[116:117] op_sel_hi:[1,0]
	v_mul_f32_e32 v116, -1.0, v142
	v_fmamk_f32 v117, v127, 0x3f800000, v116
	v_exp_f32_e32 v127, v117
	v_fmamk_f32 v117, v131, 0x3f800000, v116
	v_exp_f32_e32 v131, v117
	v_fmamk_f32 v117, v133, 0x3f800000, v116
	v_exp_f32_e32 v133, v117
	v_fmamk_f32 v117, v135, 0x3f800000, v116
	v_exp_f32_e32 v135, v117
	v_fmamk_f32 v137, v137, 0x3f800000, v116
	v_add_f32_e32 v117, 0, v127
	v_exp_f32_e32 v137, v137
	v_fmamk_f32 v138, v138, 0x3f800000, v116
	v_add_f32_e32 v117, v131, v117
	v_exp_f32_e32 v138, v138
	v_fmamk_f32 v139, v139, 0x3f800000, v116
	v_add_f32_e32 v117, v133, v117
	v_exp_f32_e32 v139, v139
	v_fmamk_f32 v140, v140, 0x3f800000, v116
	v_add_f32_e32 v117, v135, v117
	v_exp_f32_e32 v140, v140
	v_fmamk_f32 v123, v123, 0x3f800000, v116
	v_add_f32_e32 v117, v137, v117
	v_exp_f32_e32 v123, v123
	v_fmamk_f32 v124, v124, 0x3f800000, v116
	v_add_f32_e32 v117, v138, v117
	v_exp_f32_e32 v124, v124
	v_fmamk_f32 v125, v125, 0x3f800000, v116
	v_add_f32_e32 v117, v139, v117
	v_exp_f32_e32 v125, v125
	v_fmamk_f32 v126, v126, 0x3f800000, v116
	v_add_f32_e32 v117, v140, v117
	v_exp_f32_e32 v126, v126
	v_fmamk_f32 v130, v130, 0x3f800000, v116
	v_add_f32_e32 v117, v123, v117
	v_exp_f32_e32 v130, v130
	v_fmamk_f32 v132, v132, 0x3f800000, v116
	v_add_f32_e32 v117, v124, v117
	v_exp_f32_e32 v132, v132
	v_fmamk_f32 v134, v134, 0x3f800000, v116
	v_add_f32_e32 v117, v125, v117
	v_exp_f32_e32 v134, v134
	v_fmac_f32_e32 v116, 1.0, v136
	v_add_f32_e32 v117, v126, v117
	v_exp_f32_e32 v136, v116
	v_add_f32_e32 v116, v130, v117
	v_add_f32_e32 v116, v132, v116
	v_add_f32_e32 v116, v134, v116
	v_add_f32_e32 v141, v136, v116
	v_cmp_lt_f32_e32 vcc, 0xec4ecb8f, v142
	v_sub_f32_e32 v230, v142, v220
	s_nop 0
	v_cndmask_b32_e32 v231, 0, v142, vcc
	v_mov_b32_e32 v116, v230
	v_cndmask_b32_e64 v228, v228, 0, vcc
	v_sub_f32_e32 v220, v220, v231
	v_sub_f32_e32 v221, v221, v231
	v_sub_f32_e32 v222, v222, v231
	v_sub_f32_e32 v223, v223, v231
	s_branch .Lsf_2004

.Lsf_2004:
	v_cndmask_b32_e64 v155, v100, v207, s[4:5]
	v_cndmask_b32_e64 v154, v101, v207, s[4:5]
	v_add_f32_e32 v118, v118, v141
	v_cndmask_b32_e64 v143, v105, v207, s[4:5]
	v_cndmask_b32_e64 v141, v107, v207, s[4:5]
	v_max_f32_e32 v105, v154, v154
	v_max_f32_e32 v107, v155, v155
	v_cndmask_b32_e64 v153, v102, v207, s[4:5]
	v_cndmask_b32_e64 v152, v103, v207, s[4:5]
	v_max_f32_e32 v105, v107, v105
	v_cndmask_b32_e64 v151, v104, v207, s[4:5]
	v_max3_f32 v105, v105, v153, v152
	v_cndmask_b32_e64 v142, v106, v207, s[4:5]
	v_max3_f32 v105, v105, v151, v143
	v_cndmask_b32_e64 v101, v108, v207, s[4:5]
	v_cndmask_b32_e64 v102, v109, v207, s[4:5]
	v_max3_f32 v105, v105, v142, v141
	v_cndmask_b32_e64 v103, v110, v207, s[4:5]
	v_cndmask_b32_e64 v104, v111, v207, s[4:5]
	v_max3_f32 v105, v105, v101, v102
	v_cndmask_b32_e64 v106, v112, v207, s[4:5]
	v_cndmask_b32_e64 v108, v113, v207, s[4:5]
	v_max3_f32 v105, v105, v103, v104
	v_cndmask_b32_e64 v110, v114, v207, s[4:5]
	v_cndmask_b32_e64 v100, v115, v207, s[4:5]
	v_max3_f32 v105, v105, v106, v108
	v_max3_f32 v105, v105, v110, v100
	v_sub_f32_e32 v107, v105, v229

	v_cmp_lt_f32_e32 vcc, s42, v107
	s_cbranch_vccz .Lsf_2006
	v_mov_b32_e32 v107, v105
	s_nop 1
	v_permlane16_swap_b32_e32 v105, v107
	v_max_f32_e32 v105, v107, v105
	v_mov_b32_e32 v107, v105
	s_nop 1
	v_permlane32_swap_b32_e32 v105, v107
	v_max3_f32 v105, v229, v105, v107
	v_sub_f32_e32 v107, v229, v105

	v_exp_f32_e32 v112, v107
	v_cmp_lt_f32_e32 vcc, 0xec4ecb8f, v105
	v_sub_f32_e32 v230, v105, v224
	s_nop 0
	v_cndmask_b32_e32 v231, 0, v105, vcc
	v_mov_b32_e32 v117, v230
	v_cndmask_b32_e64 v229, v229, 0, vcc
	v_sub_f32_e32 v224, v224, v231
	v_sub_f32_e32 v225, v225, v231
	v_sub_f32_e32 v226, v226, v231
	v_sub_f32_e32 v227, v227, v231
	v_mul_f32_e32 v119, v119, v112
	v_pk_mul_f32 v[66:67], v[66:67], v[112:113] op_sel_hi:[1,0]
	v_pk_mul_f32 v[64:65], v[64:65], v[112:113] op_sel_hi:[1,0]
	v_pk_mul_f32 v[70:71], v[70:71], v[112:113] op_sel_hi:[1,0]
	v_pk_mul_f32 v[68:69], v[68:69], v[112:113] op_sel_hi:[1,0]
	v_pk_mul_f32 v[74:75], v[74:75], v[112:113] op_sel_hi:[1,0]
	v_pk_mul_f32 v[72:73], v[72:73], v[112:113] op_sel_hi:[1,0]
	v_pk_mul_f32 v[78:79], v[78:79], v[112:113] op_sel_hi:[1,0]
	v_pk_mul_f32 v[76:77], v[76:77], v[112:113] op_sel_hi:[1,0]
	v_mul_f32_e32 v112, -1.0, v105
	v_fmamk_f32 v105, v155, 0x3f800000, v112
	v_exp_f32_e32 v105, v105
	v_fmamk_f32 v107, v154, 0x3f800000, v112
	v_exp_f32_e32 v107, v107
	v_fmamk_f32 v109, v153, 0x3f800000, v112
	v_exp_f32_e32 v109, v109
	v_fmamk_f32 v111, v152, 0x3f800000, v112
	v_exp_f32_e32 v111, v111
	v_add_f32_e32 v113, v107, v105
	v_add_f32_e32 v113, v109, v113
	v_add_f32_e32 v152, v111, v113
	v_fmamk_f32 v113, v151, 0x3f800000, v112
	v_exp_f32_e32 v113, v113
	v_fmamk_f32 v114, v143, 0x3f800000, v112
	v_exp_f32_e32 v114, v114
	v_fmamk_f32 v115, v142, 0x3f800000, v112
	v_exp_f32_e32 v115, v115
	v_fmamk_f32 v141, v141, 0x3f800000, v112
	v_exp_f32_e32 v141, v141
	v_fmamk_f32 v101, v101, 0x3f800000, v112
	v_add_f32_e32 v142, v113, v152
	v_exp_f32_e32 v101, v101
	v_fmamk_f32 v102, v102, 0x3f800000, v112
	v_add_f32_e32 v142, v114, v142
	v_exp_f32_e32 v102, v102
	v_fmamk_f32 v103, v103, 0x3f800000, v112
	v_add_f32_e32 v142, v115, v142
	v_exp_f32_e32 v103, v103
	v_fmamk_f32 v104, v104, 0x3f800000, v112
	v_add_f32_e32 v142, v141, v142
	v_exp_f32_e32 v104, v104
	v_fmamk_f32 v106, v106, 0x3f800000, v112
	v_add_f32_e32 v142, v101, v142
	v_exp_f32_e32 v106, v106
	v_fmamk_f32 v108, v108, 0x3f800000, v112
	v_fmamk_f32 v110, v110, 0x3f800000, v112
	v_fmac_f32_e32 v112, 1.0, v100
	v_add_f32_e32 v142, v102, v142
	v_exp_f32_e32 v108, v108
	v_exp_f32_e32 v110, v110
	v_exp_f32_e32 v112, v112
	v_add_f32_e32 v142, v103, v142
	v_add_f32_e32 v142, v104, v142
	v_add_f32_e32 v100, v106, v142
	s_branch .Lsf_2007
